# s_setprio 1 while a wave is in the G1 / G2 gather row loops, 0 in expert selection / finalize
# speedup vs baseline: 1.0021x; 1.0021x over previous
.LBB0_977:
	s_setprio 0
	s_waitcnt lgkmcnt(0)
	ds_read2st64_b64 v[0:3], v135 offset0:6 offset1:8
	v_lshlrev_b64 v[4:5], 9, v[116:117]
	v_mov_b32_e32 v116, v141
	s_waitcnt lgkmcnt(0)
	v_fma_mixlo_f16 v2, v2, s62, 0
	v_fma_mixhi_f16 v3, v3, s62, 0
	v_lshl_or_b32 v0, v2, 16, v0
	v_and_or_b32 v1, v3, s50, v1
	v_lshl_add_u64 v[2:3], v[122:123], 0, v[4:5]
	global_store_dwordx2 v[2:3], v[0:1], off
	s_waitcnt lgkmcnt(0)
	s_andn2_b64 exec, exec, s[34:35]
	s_cbranch_execz .LBB0_1038

.LBB0_1012:
	s_or_b64 exec, exec, s[42:43]
	v_ashrrev_i32_e32 v117, 31, v116
	v_lshlrev_b64 v[0:1], 11, v[116:117]
	s_waitcnt lgkmcnt(0)
	v_lshl_add_u64 v[0:1], v[120:121], 0, v[0:1]
	global_load_dwordx2 v[2:3], v[0:1], off
	global_load_dwordx2 v[4:5], v[0:1], off offset:256
	global_load_dwordx2 v[6:7], v[0:1], off offset:512
	global_load_dwordx2 v[8:9], v[0:1], off offset:768
	global_load_dwordx2 v[10:11], v[0:1], off offset:1024
	global_load_dwordx2 v[12:13], v[0:1], off offset:1280
	global_load_dwordx2 v[14:15], v[0:1], off offset:1536
	s_nop 0
	global_load_dwordx2 v[0:1], v[0:1], off offset:1792
	s_movk_i32 s63, 0xffe0
	v_mov_b32_e32 v183, v134
	s_waitcnt vmcnt(7)
	v_lshlrev_b32_e32 v16, 16, v2
	v_and_b32_e32 v2, 0xffff0000, v2
	v_lshlrev_b32_e32 v17, 16, v3
	v_and_b32_e32 v3, 0xffff0000, v3
	s_waitcnt vmcnt(6)
	v_lshlrev_b32_e32 v18, 16, v4
	v_and_b32_e32 v4, 0xffff0000, v4
	v_lshlrev_b32_e32 v19, 16, v5
	v_and_b32_e32 v5, 0xffff0000, v5
	s_waitcnt vmcnt(5)
	v_lshlrev_b32_e32 v20, 16, v6
	v_and_b32_e32 v6, 0xffff0000, v6
	v_lshlrev_b32_e32 v21, 16, v7
	v_and_b32_e32 v7, 0xffff0000, v7
	s_waitcnt vmcnt(4)
	v_lshlrev_b32_e32 v22, 16, v8
	v_and_b32_e32 v8, 0xffff0000, v8
	v_lshlrev_b32_e32 v23, 16, v9
	v_and_b32_e32 v9, 0xffff0000, v9
	s_waitcnt vmcnt(3)
	v_lshlrev_b32_e32 v24, 16, v10
	v_and_b32_e32 v10, 0xffff0000, v10
	v_lshlrev_b32_e32 v25, 16, v11
	v_and_b32_e32 v11, 0xffff0000, v11
	s_waitcnt vmcnt(2)
	v_lshlrev_b32_e32 v26, 16, v12
	v_and_b32_e32 v12, 0xffff0000, v12
	v_lshlrev_b32_e32 v27, 16, v13
	v_and_b32_e32 v13, 0xffff0000, v13
	s_waitcnt vmcnt(1)
	v_lshlrev_b32_e32 v28, 16, v14
	v_and_b32_e32 v14, 0xffff0000, v14
	v_lshlrev_b32_e32 v29, 16, v15
	v_and_b32_e32 v15, 0xffff0000, v15
	s_waitcnt vmcnt(0)
	v_lshlrev_b32_e32 v30, 16, v0
	v_and_b32_e32 v0, 0xffff0000, v0
	v_lshlrev_b32_e32 v31, 16, v1
	v_and_b32_e32 v1, 0xffff0000, v1
	v_cvt_pk_f16_f32 v166, v16, v2
	v_cvt_pk_f16_f32 v167, v17, v3
	v_cvt_pk_f16_f32 v168, v18, v4
	v_cvt_pk_f16_f32 v169, v19, v5
	v_cvt_pk_f16_f32 v170, v20, v6
	v_cvt_pk_f16_f32 v171, v21, v7
	v_cvt_pk_f16_f32 v172, v22, v8
	v_cvt_pk_f16_f32 v173, v23, v9
	v_cvt_pk_f16_f32 v174, v24, v10
	v_cvt_pk_f16_f32 v175, v25, v11
	v_cvt_pk_f16_f32 v177, v26, v12
	v_cvt_pk_f16_f32 v178, v27, v13
	v_cvt_pk_f16_f32 v179, v28, v14
	v_cvt_pk_f16_f32 v180, v29, v15
	v_cvt_pk_f16_f32 v181, v30, v0
	v_cvt_pk_f16_f32 v182, v31, v1
	s_setprio 1
	s_branch .LBB0_1015

.LBB0_1093:
	s_setprio 1
	ds_read_b128 v[88:91], v101
	ds_read_b128 v[84:87], v101 offset:16
	ds_read_b128 v[80:83], v101 offset:32
	ds_read_b128 v[76:79], v101 offset:48
	s_add_i32 s24, s24, 32
	s_waitcnt lgkmcnt(3)
	v_and_b32_e32 v0, 0xffff, v88
	v_and_b32_e32 v1, 0xffff, v89
	v_and_b32_e32 v2, 0xffff, v90
	v_and_b32_e32 v3, 0xffff, v91
	s_waitcnt lgkmcnt(2)
	v_and_b32_e32 v4, 0xffff, v84
	v_and_b32_e32 v5, 0xffff, v85
	v_and_b32_e32 v6, 0xffff, v86
	v_and_b32_e32 v7, 0xffff, v87
	s_waitcnt lgkmcnt(1)
	v_and_b32_e32 v8, 0xffff, v80
	v_and_b32_e32 v9, 0xffff, v81
	v_and_b32_e32 v11, 0xffff, v83
	s_waitcnt lgkmcnt(0)
	v_and_b32_e32 v12, 0xffff, v76
	v_and_b32_e32 v13, 0xffff, v77
	v_and_b32_e32 v10, 0xffff, v82
	v_and_b32_e32 v14, 0xffff, v78
	v_and_b32_e32 v15, 0xffff, v79
	v_mad_u32_u24 v16, v0, s22, v116
	v_mad_u32_u24 v17, v1, s22, v117
	v_mad_u32_u24 v18, v2, s22, v116
	v_mad_u32_u24 v19, v3, s22, v116
	v_mad_u32_u24 v22, v4, s22, v116
	v_mad_u32_u24 v23, v5, s22, v116
	v_mad_u32_u24 v24, v6, s22, v116
	v_mad_u32_u24 v25, v7, s22, v116
	v_mad_u32_u24 v26, v8, s22, v116
	v_mad_u32_u24 v27, v9, s22, v116
	v_mad_u32_u24 v204, v11, s22, v116
	v_mad_u32_u24 v210, v12, s22, v116
	v_mad_u32_u24 v216, v13, s22, v116
	v_mad_u32_u24 v0, v0, s22, v117
	v_mad_u32_u24 v2, v2, s22, v117
	v_mad_u32_u24 v3, v3, s22, v117
	v_mad_u32_u24 v4, v4, s22, v117
	v_mad_u32_u24 v5, v5, s22, v117
	v_mad_u32_u24 v6, v6, s22, v117
	v_mad_u32_u24 v7, v7, s22, v117
	v_mad_u32_u24 v8, v8, s22, v117
	v_mad_u32_u24 v9, v9, s22, v117
	v_mad_u32_u24 v137, v10, s22, v116
	v_mad_u32_u24 v10, v10, s22, v117
	v_mad_u32_u24 v11, v11, s22, v117
	v_mad_u32_u24 v12, v12, s22, v117
	v_mad_u32_u24 v13, v13, s22, v117
	v_mad_u32_u24 v222, v14, s22, v116
	v_mad_u32_u24 v14, v14, s22, v117
	v_mad_u32_u24 v223, v15, s22, v116
	v_mad_u32_u24 v15, v15, s22, v117
	v_mad_u32_u24 v1, v1, s22, v116
	global_load_dwordx4 v[138:141], v16, s[2:3]
	global_load_dwordx2 v[142:143], v0, s[2:3]
	global_load_dwordx4 v[144:147], v1, s[2:3]
	global_load_dwordx2 v[148:149], v17, s[2:3]
	global_load_dwordx4 v[150:153], v18, s[2:3]
	global_load_dwordx2 v[154:155], v2, s[2:3]
	global_load_dwordx4 v[156:159], v19, s[2:3]
	global_load_dwordx2 v[160:161], v3, s[2:3]
	global_load_dwordx2 v[20:21], v15, s[2:3]
	global_load_dwordx4 v[162:165], v22, s[2:3]
	global_load_dwordx2 v[166:167], v4, s[2:3]
	global_load_dwordx4 v[168:171], v23, s[2:3]
	global_load_dwordx2 v[172:173], v5, s[2:3]
	global_load_dwordx4 v[174:177], v24, s[2:3]
	global_load_dwordx2 v[178:179], v6, s[2:3]
	global_load_dwordx4 v[180:183], v25, s[2:3]
	global_load_dwordx2 v[184:185], v7, s[2:3]
	global_load_dwordx4 v[186:189], v26, s[2:3]
	global_load_dwordx2 v[190:191], v8, s[2:3]
	global_load_dwordx4 v[192:195], v27, s[2:3]
	global_load_dwordx2 v[196:197], v9, s[2:3]
	global_load_dwordx4 v[198:201], v137, s[2:3]
	global_load_dwordx2 v[202:203], v10, s[2:3]
	s_nop 0
	global_load_dwordx4 v[204:207], v204, s[2:3]
	s_nop 0
	global_load_dwordx2 v[208:209], v11, s[2:3]
	s_nop 0
	global_load_dwordx4 v[210:213], v210, s[2:3]
	s_nop 0
	global_load_dwordx2 v[214:215], v12, s[2:3]
	s_nop 0
	global_load_dwordx4 v[216:219], v216, s[2:3]
	s_nop 0
	global_load_dwordx2 v[220:221], v13, s[2:3]
	global_load_dwordx4 v[22:25], v222, s[2:3]
	global_load_dwordx2 v[26:27], v14, s[2:3]
	global_load_dwordx4 v[16:19], v223, s[2:3]
	v_add_u32_e32 v101, 0x80, v101
	s_cmpk_lt_u32 s24, 0x60
	s_waitcnt vmcnt(30)
	v_cvt_scalef32_pk32_f16_fp6 v[0:15], v[138:143], 1.0
	v_pk_fma_f16 v133, v88, v0, v133 op_sel:[1,0,0]
	v_pk_fma_f16 v131, v88, v1, v131 op_sel:[1,0,0]
	v_pk_fma_f16 v129, v88, v2, v129 op_sel:[1,0,0]
	v_pk_fma_f16 v128, v88, v3, v128 op_sel:[1,0,0]
	v_pk_fma_f16 v127, v88, v4, v127 op_sel:[1,0,0]
	v_pk_fma_f16 v125, v88, v5, v125 op_sel:[1,0,0]
	v_pk_fma_f16 v123, v88, v6, v123 op_sel:[1,0,0]
	v_pk_fma_f16 v121, v88, v7, v121 op_sel:[1,0,0]
	v_pk_fma_f16 v136, v88, v8, v136 op_sel:[1,0,0]
	v_pk_fma_f16 v135, v88, v9, v135 op_sel:[1,0,0]
	v_pk_fma_f16 v134, v88, v10, v134 op_sel:[1,0,0]
	v_pk_fma_f16 v132, v88, v11, v132 op_sel:[1,0,0]
	v_pk_fma_f16 v130, v88, v12, v130 op_sel:[1,0,0]
	v_pk_fma_f16 v126, v88, v13, v126 op_sel:[1,0,0]
	v_pk_fma_f16 v124, v88, v14, v124 op_sel:[1,0,0]
	v_pk_fma_f16 v88, v88, v15, v122 op_sel:[1,0,0]
	s_waitcnt vmcnt(29)
	s_waitcnt vmcnt(28)
	v_cvt_scalef32_pk32_f16_fp6 v[0:15], v[144:149], 1.0
	v_pk_fma_f16 v122, v89, v0, v133 op_sel:[1,0,0]
	v_pk_fma_f16 v131, v89, v1, v131 op_sel:[1,0,0]
	v_pk_fma_f16 v129, v89, v2, v129 op_sel:[1,0,0]
	v_pk_fma_f16 v128, v89, v3, v128 op_sel:[1,0,0]
	v_pk_fma_f16 v127, v89, v4, v127 op_sel:[1,0,0]
	v_pk_fma_f16 v125, v89, v5, v125 op_sel:[1,0,0]
	v_pk_fma_f16 v123, v89, v6, v123 op_sel:[1,0,0]
	v_pk_fma_f16 v121, v89, v7, v121 op_sel:[1,0,0]
	v_pk_fma_f16 v133, v89, v8, v136 op_sel:[1,0,0]
	v_pk_fma_f16 v135, v89, v9, v135 op_sel:[1,0,0]
	v_pk_fma_f16 v134, v89, v10, v134 op_sel:[1,0,0]
	v_pk_fma_f16 v132, v89, v11, v132 op_sel:[1,0,0]
	v_pk_fma_f16 v130, v89, v12, v130 op_sel:[1,0,0]
	v_pk_fma_f16 v126, v89, v13, v126 op_sel:[1,0,0]
	v_pk_fma_f16 v124, v89, v14, v124 op_sel:[1,0,0]
	v_pk_fma_f16 v88, v89, v15, v88 op_sel:[1,0,0]
	s_waitcnt vmcnt(27)
	s_waitcnt vmcnt(26)
	v_cvt_scalef32_pk32_f16_fp6 v[0:15], v[150:155], 1.0
	v_pk_fma_f16 v89, v90, v0, v122 op_sel:[1,0,0]
	v_pk_fma_f16 v122, v90, v1, v131 op_sel:[1,0,0]
	v_pk_fma_f16 v129, v90, v2, v129 op_sel:[1,0,0]
	v_pk_fma_f16 v128, v90, v3, v128 op_sel:[1,0,0]
	v_pk_fma_f16 v127, v90, v4, v127 op_sel:[1,0,0]
	v_pk_fma_f16 v125, v90, v5, v125 op_sel:[1,0,0]
	v_pk_fma_f16 v123, v90, v6, v123 op_sel:[1,0,0]
	v_pk_fma_f16 v121, v90, v7, v121 op_sel:[1,0,0]
	v_pk_fma_f16 v131, v90, v8, v133 op_sel:[1,0,0]
	v_pk_fma_f16 v133, v90, v9, v135 op_sel:[1,0,0]
	v_pk_fma_f16 v134, v90, v10, v134 op_sel:[1,0,0]
	v_pk_fma_f16 v132, v90, v11, v132 op_sel:[1,0,0]
	v_pk_fma_f16 v130, v90, v12, v130 op_sel:[1,0,0]
	v_pk_fma_f16 v126, v90, v13, v126 op_sel:[1,0,0]
	v_pk_fma_f16 v124, v90, v14, v124 op_sel:[1,0,0]
	v_pk_fma_f16 v88, v90, v15, v88 op_sel:[1,0,0]
	s_waitcnt vmcnt(25)
	s_waitcnt vmcnt(24)
	v_cvt_scalef32_pk32_f16_fp6 v[0:15], v[156:161], 1.0
	v_pk_fma_f16 v89, v91, v0, v89 op_sel:[1,0,0]
	v_pk_fma_f16 v90, v91, v1, v122 op_sel:[1,0,0]
	v_pk_fma_f16 v122, v91, v2, v129 op_sel:[1,0,0]
	v_pk_fma_f16 v128, v91, v3, v128 op_sel:[1,0,0]
	v_pk_fma_f16 v127, v91, v4, v127 op_sel:[1,0,0]
	v_pk_fma_f16 v125, v91, v5, v125 op_sel:[1,0,0]
	v_pk_fma_f16 v123, v91, v6, v123 op_sel:[1,0,0]
	v_pk_fma_f16 v121, v91, v7, v121 op_sel:[1,0,0]
	v_pk_fma_f16 v129, v91, v8, v131 op_sel:[1,0,0]
	v_pk_fma_f16 v131, v91, v9, v133 op_sel:[1,0,0]
	v_pk_fma_f16 v133, v91, v10, v134 op_sel:[1,0,0]
	v_pk_fma_f16 v132, v91, v11, v132 op_sel:[1,0,0]
	v_pk_fma_f16 v130, v91, v12, v130 op_sel:[1,0,0]
	v_pk_fma_f16 v126, v91, v13, v126 op_sel:[1,0,0]
	v_pk_fma_f16 v124, v91, v14, v124 op_sel:[1,0,0]
	v_pk_fma_f16 v88, v91, v15, v88 op_sel:[1,0,0]
	s_waitcnt vmcnt(22)
	s_waitcnt vmcnt(21)
	v_cvt_scalef32_pk32_f16_fp6 v[0:15], v[162:167], 1.0
	v_pk_fma_f16 v89, v84, v0, v89 op_sel:[1,0,0]
	v_pk_fma_f16 v90, v84, v1, v90 op_sel:[1,0,0]
	v_pk_fma_f16 v91, v84, v2, v122 op_sel:[1,0,0]
	v_pk_fma_f16 v122, v84, v3, v128 op_sel:[1,0,0]
	v_pk_fma_f16 v127, v84, v4, v127 op_sel:[1,0,0]
	v_pk_fma_f16 v125, v84, v5, v125 op_sel:[1,0,0]
	v_pk_fma_f16 v123, v84, v6, v123 op_sel:[1,0,0]
	v_pk_fma_f16 v121, v84, v7, v121 op_sel:[1,0,0]
	v_pk_fma_f16 v128, v84, v8, v129 op_sel:[1,0,0]
	v_pk_fma_f16 v129, v84, v9, v131 op_sel:[1,0,0]
	v_pk_fma_f16 v131, v84, v10, v133 op_sel:[1,0,0]
	v_pk_fma_f16 v132, v84, v11, v132 op_sel:[1,0,0]
	v_pk_fma_f16 v130, v84, v12, v130 op_sel:[1,0,0]
	v_pk_fma_f16 v126, v84, v13, v126 op_sel:[1,0,0]
	v_pk_fma_f16 v124, v84, v14, v124 op_sel:[1,0,0]
	v_pk_fma_f16 v84, v84, v15, v88 op_sel:[1,0,0]
	s_waitcnt vmcnt(20)
	s_waitcnt vmcnt(19)
	v_cvt_scalef32_pk32_f16_fp6 v[0:15], v[168:173], 1.0
	v_pk_fma_f16 v88, v85, v0, v89 op_sel:[1,0,0]
	v_pk_fma_f16 v89, v85, v1, v90 op_sel:[1,0,0]
	v_pk_fma_f16 v90, v85, v2, v91 op_sel:[1,0,0]
	v_pk_fma_f16 v91, v85, v3, v122 op_sel:[1,0,0]
	v_pk_fma_f16 v122, v85, v4, v127 op_sel:[1,0,0]
	v_pk_fma_f16 v125, v85, v5, v125 op_sel:[1,0,0]
	v_pk_fma_f16 v123, v85, v6, v123 op_sel:[1,0,0]
	v_pk_fma_f16 v121, v85, v7, v121 op_sel:[1,0,0]
	v_pk_fma_f16 v127, v85, v8, v128 op_sel:[1,0,0]
	v_pk_fma_f16 v128, v85, v9, v129 op_sel:[1,0,0]
	v_pk_fma_f16 v129, v85, v10, v131 op_sel:[1,0,0]
	v_pk_fma_f16 v131, v85, v11, v132 op_sel:[1,0,0]
	v_pk_fma_f16 v130, v85, v12, v130 op_sel:[1,0,0]
	v_pk_fma_f16 v126, v85, v13, v126 op_sel:[1,0,0]
	v_pk_fma_f16 v124, v85, v14, v124 op_sel:[1,0,0]
	v_pk_fma_f16 v84, v85, v15, v84 op_sel:[1,0,0]
	s_waitcnt vmcnt(18)
	s_waitcnt vmcnt(17)
	v_cvt_scalef32_pk32_f16_fp6 v[0:15], v[174:179], 1.0
	v_pk_fma_f16 v85, v86, v0, v88 op_sel:[1,0,0]
	v_pk_fma_f16 v88, v86, v1, v89 op_sel:[1,0,0]
	v_pk_fma_f16 v89, v86, v2, v90 op_sel:[1,0,0]
	v_pk_fma_f16 v90, v86, v3, v91 op_sel:[1,0,0]
	v_pk_fma_f16 v91, v86, v4, v122 op_sel:[1,0,0]
	v_pk_fma_f16 v122, v86, v5, v125 op_sel:[1,0,0]
	v_pk_fma_f16 v123, v86, v6, v123 op_sel:[1,0,0]
	v_pk_fma_f16 v121, v86, v7, v121 op_sel:[1,0,0]
	v_pk_fma_f16 v125, v86, v8, v127 op_sel:[1,0,0]
	v_pk_fma_f16 v127, v86, v9, v128 op_sel:[1,0,0]
	v_pk_fma_f16 v128, v86, v10, v129 op_sel:[1,0,0]
	v_pk_fma_f16 v129, v86, v11, v131 op_sel:[1,0,0]
	v_pk_fma_f16 v130, v86, v12, v130 op_sel:[1,0,0]
	v_pk_fma_f16 v126, v86, v13, v126 op_sel:[1,0,0]
	v_pk_fma_f16 v124, v86, v14, v124 op_sel:[1,0,0]
	v_pk_fma_f16 v84, v86, v15, v84 op_sel:[1,0,0]
	s_waitcnt vmcnt(16)
	s_waitcnt vmcnt(15)
	v_cvt_scalef32_pk32_f16_fp6 v[0:15], v[180:185], 1.0
	v_pk_fma_f16 v85, v87, v0, v85 op_sel:[1,0,0]
	v_pk_fma_f16 v86, v87, v1, v88 op_sel:[1,0,0]
	v_pk_fma_f16 v88, v87, v2, v89 op_sel:[1,0,0]
	v_pk_fma_f16 v89, v87, v3, v90 op_sel:[1,0,0]
	v_pk_fma_f16 v90, v87, v4, v91 op_sel:[1,0,0]
	v_pk_fma_f16 v91, v87, v5, v122 op_sel:[1,0,0]
	v_pk_fma_f16 v122, v87, v6, v123 op_sel:[1,0,0]
	v_pk_fma_f16 v121, v87, v7, v121 op_sel:[1,0,0]
	v_pk_fma_f16 v123, v87, v8, v125 op_sel:[1,0,0]
	v_pk_fma_f16 v125, v87, v9, v127 op_sel:[1,0,0]
	v_pk_fma_f16 v127, v87, v10, v128 op_sel:[1,0,0]
	v_pk_fma_f16 v128, v87, v11, v129 op_sel:[1,0,0]
	v_pk_fma_f16 v129, v87, v12, v130 op_sel:[1,0,0]
	v_pk_fma_f16 v126, v87, v13, v126 op_sel:[1,0,0]
	v_pk_fma_f16 v124, v87, v14, v124 op_sel:[1,0,0]
	v_pk_fma_f16 v84, v87, v15, v84 op_sel:[1,0,0]
	s_waitcnt vmcnt(14)
	s_waitcnt vmcnt(13)
	v_cvt_scalef32_pk32_f16_fp6 v[0:15], v[186:191], 1.0
	v_pk_fma_f16 v85, v80, v0, v85 op_sel:[1,0,0]
	v_pk_fma_f16 v86, v80, v1, v86 op_sel:[1,0,0]
	v_pk_fma_f16 v87, v80, v2, v88 op_sel:[1,0,0]
	v_pk_fma_f16 v88, v80, v3, v89 op_sel:[1,0,0]
	v_pk_fma_f16 v89, v80, v4, v90 op_sel:[1,0,0]
	v_pk_fma_f16 v90, v80, v5, v91 op_sel:[1,0,0]
	v_pk_fma_f16 v91, v80, v6, v122 op_sel:[1,0,0]
	v_pk_fma_f16 v121, v80, v7, v121 op_sel:[1,0,0]
	v_pk_fma_f16 v122, v80, v8, v123 op_sel:[1,0,0]
	v_pk_fma_f16 v123, v80, v9, v125 op_sel:[1,0,0]
	v_pk_fma_f16 v125, v80, v10, v127 op_sel:[1,0,0]
	v_pk_fma_f16 v127, v80, v11, v128 op_sel:[1,0,0]
	v_pk_fma_f16 v128, v80, v12, v129 op_sel:[1,0,0]
	v_pk_fma_f16 v126, v80, v13, v126 op_sel:[1,0,0]
	v_pk_fma_f16 v124, v80, v14, v124 op_sel:[1,0,0]
	v_pk_fma_f16 v80, v80, v15, v84 op_sel:[1,0,0]
	s_waitcnt vmcnt(12)
	s_waitcnt vmcnt(11)
	v_cvt_scalef32_pk32_f16_fp6 v[0:15], v[192:197], 1.0
	v_pk_fma_f16 v84, v81, v0, v85 op_sel:[1,0,0]
	v_pk_fma_f16 v85, v81, v1, v86 op_sel:[1,0,0]
	v_pk_fma_f16 v86, v81, v2, v87 op_sel:[1,0,0]
	v_pk_fma_f16 v87, v81, v3, v88 op_sel:[1,0,0]
	v_pk_fma_f16 v88, v81, v4, v89 op_sel:[1,0,0]
	v_pk_fma_f16 v89, v81, v5, v90 op_sel:[1,0,0]
	v_pk_fma_f16 v90, v81, v6, v91 op_sel:[1,0,0]
	v_pk_fma_f16 v91, v81, v7, v121 op_sel:[1,0,0]
	v_pk_fma_f16 v121, v81, v8, v122 op_sel:[1,0,0]
	v_pk_fma_f16 v122, v81, v9, v123 op_sel:[1,0,0]
	v_pk_fma_f16 v123, v81, v10, v125 op_sel:[1,0,0]
	v_pk_fma_f16 v125, v81, v11, v127 op_sel:[1,0,0]
	v_pk_fma_f16 v127, v81, v12, v128 op_sel:[1,0,0]
	v_pk_fma_f16 v126, v81, v13, v126 op_sel:[1,0,0]
	v_pk_fma_f16 v124, v81, v14, v124 op_sel:[1,0,0]
	v_pk_fma_f16 v80, v81, v15, v80 op_sel:[1,0,0]
	s_waitcnt vmcnt(10)
	s_waitcnt vmcnt(9)
	v_cvt_scalef32_pk32_f16_fp6 v[0:15], v[198:203], 1.0
	v_pk_fma_f16 v81, v82, v0, v84 op_sel:[1,0,0]
	v_pk_fma_f16 v84, v82, v1, v85 op_sel:[1,0,0]
	v_pk_fma_f16 v85, v82, v2, v86 op_sel:[1,0,0]
	v_pk_fma_f16 v86, v82, v3, v87 op_sel:[1,0,0]
	v_pk_fma_f16 v87, v82, v4, v88 op_sel:[1,0,0]
	v_pk_fma_f16 v88, v82, v5, v89 op_sel:[1,0,0]
	v_pk_fma_f16 v89, v82, v6, v90 op_sel:[1,0,0]
	v_pk_fma_f16 v90, v82, v7, v91 op_sel:[1,0,0]
	v_pk_fma_f16 v91, v82, v8, v121 op_sel:[1,0,0]
	v_pk_fma_f16 v121, v82, v9, v122 op_sel:[1,0,0]
	v_pk_fma_f16 v122, v82, v10, v123 op_sel:[1,0,0]
	v_pk_fma_f16 v123, v82, v11, v125 op_sel:[1,0,0]
	v_pk_fma_f16 v125, v82, v12, v127 op_sel:[1,0,0]
	v_pk_fma_f16 v126, v82, v13, v126 op_sel:[1,0,0]
	v_pk_fma_f16 v124, v82, v14, v124 op_sel:[1,0,0]
	v_pk_fma_f16 v80, v82, v15, v80 op_sel:[1,0,0]
	s_waitcnt vmcnt(8)
	s_waitcnt vmcnt(7)
	v_cvt_scalef32_pk32_f16_fp6 v[0:15], v[204:209], 1.0
	v_pk_fma_f16 v81, v83, v0, v81 op_sel:[1,0,0]
	v_pk_fma_f16 v82, v83, v1, v84 op_sel:[1,0,0]
	v_pk_fma_f16 v84, v83, v2, v85 op_sel:[1,0,0]
	v_pk_fma_f16 v85, v83, v3, v86 op_sel:[1,0,0]
	v_pk_fma_f16 v86, v83, v4, v87 op_sel:[1,0,0]
	v_pk_fma_f16 v87, v83, v5, v88 op_sel:[1,0,0]
	v_pk_fma_f16 v88, v83, v6, v89 op_sel:[1,0,0]
	v_pk_fma_f16 v89, v83, v7, v90 op_sel:[1,0,0]
	v_pk_fma_f16 v90, v83, v8, v91 op_sel:[1,0,0]
	v_pk_fma_f16 v91, v83, v9, v121 op_sel:[1,0,0]
	v_pk_fma_f16 v121, v83, v10, v122 op_sel:[1,0,0]
	v_pk_fma_f16 v122, v83, v11, v123 op_sel:[1,0,0]
	v_pk_fma_f16 v123, v83, v12, v125 op_sel:[1,0,0]
	v_pk_fma_f16 v125, v83, v13, v126 op_sel:[1,0,0]
	v_pk_fma_f16 v124, v83, v14, v124 op_sel:[1,0,0]
	v_pk_fma_f16 v80, v83, v15, v80 op_sel:[1,0,0]
	s_waitcnt vmcnt(6)
	s_waitcnt vmcnt(5)
	v_cvt_scalef32_pk32_f16_fp6 v[0:15], v[210:215], 1.0
	v_pk_fma_f16 v81, v76, v0, v81 op_sel:[1,0,0]
	v_pk_fma_f16 v82, v76, v1, v82 op_sel:[1,0,0]
	v_pk_fma_f16 v83, v76, v2, v84 op_sel:[1,0,0]
	v_pk_fma_f16 v84, v76, v3, v85 op_sel:[1,0,0]
	v_pk_fma_f16 v85, v76, v4, v86 op_sel:[1,0,0]
	v_pk_fma_f16 v86, v76, v5, v87 op_sel:[1,0,0]
	v_pk_fma_f16 v87, v76, v6, v88 op_sel:[1,0,0]
	v_pk_fma_f16 v88, v76, v7, v89 op_sel:[1,0,0]
	v_pk_fma_f16 v89, v76, v8, v90 op_sel:[1,0,0]
	v_pk_fma_f16 v90, v76, v9, v91 op_sel:[1,0,0]
	v_pk_fma_f16 v91, v76, v10, v121 op_sel:[1,0,0]
	v_pk_fma_f16 v121, v76, v11, v122 op_sel:[1,0,0]
	v_pk_fma_f16 v122, v76, v12, v123 op_sel:[1,0,0]
	v_pk_fma_f16 v123, v76, v13, v125 op_sel:[1,0,0]
	v_pk_fma_f16 v124, v76, v14, v124 op_sel:[1,0,0]
	v_pk_fma_f16 v76, v76, v15, v80 op_sel:[1,0,0]
	s_waitcnt vmcnt(4)
	s_waitcnt vmcnt(3)
	v_cvt_scalef32_pk32_f16_fp6 v[0:15], v[216:221], 1.0
	v_pk_fma_f16 v80, v77, v0, v81 op_sel:[1,0,0]
	v_pk_fma_f16 v81, v77, v1, v82 op_sel:[1,0,0]
	v_pk_fma_f16 v82, v77, v2, v83 op_sel:[1,0,0]
	v_pk_fma_f16 v83, v77, v3, v84 op_sel:[1,0,0]
	v_pk_fma_f16 v84, v77, v4, v85 op_sel:[1,0,0]
	v_pk_fma_f16 v85, v77, v5, v86 op_sel:[1,0,0]
	v_pk_fma_f16 v86, v77, v6, v87 op_sel:[1,0,0]
	v_pk_fma_f16 v87, v77, v7, v88 op_sel:[1,0,0]
	v_pk_fma_f16 v88, v77, v8, v89 op_sel:[1,0,0]
	v_pk_fma_f16 v89, v77, v9, v90 op_sel:[1,0,0]
	v_pk_fma_f16 v90, v77, v10, v91 op_sel:[1,0,0]
	v_pk_fma_f16 v91, v77, v11, v121 op_sel:[1,0,0]
	v_pk_fma_f16 v121, v77, v12, v122 op_sel:[1,0,0]
	v_pk_fma_f16 v122, v77, v13, v123 op_sel:[1,0,0]
	v_pk_fma_f16 v123, v77, v14, v124 op_sel:[1,0,0]
	v_pk_fma_f16 v76, v77, v15, v76 op_sel:[1,0,0]
	s_waitcnt vmcnt(2)
	s_waitcnt vmcnt(1)
	v_cvt_scalef32_pk32_f16_fp6 v[0:15], v[22:27], 1.0
	v_pk_fma_f16 v22, v78, v0, v80 op_sel:[1,0,0]
	v_pk_fma_f16 v23, v78, v1, v81 op_sel:[1,0,0]
	v_pk_fma_f16 v24, v78, v2, v82 op_sel:[1,0,0]
	v_pk_fma_f16 v25, v78, v3, v83 op_sel:[1,0,0]
	v_pk_fma_f16 v26, v78, v4, v84 op_sel:[1,0,0]
	v_pk_fma_f16 v27, v78, v5, v85 op_sel:[1,0,0]
	v_pk_fma_f16 v77, v78, v6, v86 op_sel:[1,0,0]
	v_pk_fma_f16 v80, v78, v7, v87 op_sel:[1,0,0]
	v_pk_fma_f16 v81, v78, v8, v88 op_sel:[1,0,0]
	v_pk_fma_f16 v82, v78, v9, v89 op_sel:[1,0,0]
	v_pk_fma_f16 v83, v78, v10, v90 op_sel:[1,0,0]
	v_pk_fma_f16 v84, v78, v11, v91 op_sel:[1,0,0]
	v_pk_fma_f16 v85, v78, v12, v121 op_sel:[1,0,0]
	v_pk_fma_f16 v86, v78, v13, v122 op_sel:[1,0,0]
	v_pk_fma_f16 v87, v78, v14, v123 op_sel:[1,0,0]
	v_pk_fma_f16 v76, v78, v15, v76 op_sel:[1,0,0]
	s_waitcnt vmcnt(0)
	s_nop 0
	v_cvt_scalef32_pk32_f16_fp6 v[0:15], v[16:21], 1.0
	v_pk_fma_f16 v133, v79, v0, v22 op_sel:[1,0,0]
	v_pk_fma_f16 v131, v79, v1, v23 op_sel:[1,0,0]
	v_pk_fma_f16 v129, v79, v2, v24 op_sel:[1,0,0]
	v_pk_fma_f16 v128, v79, v3, v25 op_sel:[1,0,0]
	v_pk_fma_f16 v127, v79, v4, v26 op_sel:[1,0,0]
	v_pk_fma_f16 v125, v79, v5, v27 op_sel:[1,0,0]
	v_pk_fma_f16 v123, v79, v6, v77 op_sel:[1,0,0]
	v_pk_fma_f16 v121, v79, v7, v80 op_sel:[1,0,0]
	v_pk_fma_f16 v136, v79, v8, v81 op_sel:[1,0,0]
	v_pk_fma_f16 v135, v79, v9, v82 op_sel:[1,0,0]
	v_pk_fma_f16 v134, v79, v10, v83 op_sel:[1,0,0]
	v_pk_fma_f16 v132, v79, v11, v84 op_sel:[1,0,0]
	v_pk_fma_f16 v130, v79, v12, v85 op_sel:[1,0,0]
	v_pk_fma_f16 v126, v79, v13, v86 op_sel:[1,0,0]
	v_pk_fma_f16 v124, v79, v14, v87 op_sel:[1,0,0]
	v_pk_fma_f16 v122, v79, v15, v76 op_sel:[1,0,0]
	s_cbranch_scc1 .LBB0_1093
	s_cmp_eq_u32 s43, 0
	s_cbranch_scc1 .Lg2_save
	s_setprio 0
	global_load_dword v82, v95, s[4:5]
	v_permlane32_swap_b32_e32 v133, v136
	v_permlane32_swap_b32_e32 v131, v135
	v_permlane32_swap_b32_e32 v129, v134
	v_cvt_f32_f16_e32 v14, v133
	v_cvt_f32_f16_sdwa v15, v133 dst_sel:DWORD dst_unused:UNUSED_PAD src0_sel:WORD_1
	v_cvt_f32_f16_e32 v16, v136
	v_cvt_f32_f16_sdwa v17, v136 dst_sel:DWORD dst_unused:UNUSED_PAD src0_sel:WORD_1
	v_cvt_f32_f16_e32 v18, v131
	v_cvt_f32_f16_sdwa v19, v131 dst_sel:DWORD dst_unused:UNUSED_PAD src0_sel:WORD_1
	v_cvt_f32_f16_e32 v20, v135
	v_cvt_f32_f16_sdwa v21, v135 dst_sel:DWORD dst_unused:UNUSED_PAD src0_sel:WORD_1
	v_cvt_f32_f16_e32 v22, v129
	v_cvt_f32_f16_sdwa v23, v129 dst_sel:DWORD dst_unused:UNUSED_PAD src0_sel:WORD_1
	v_cvt_f32_f16_e32 v24, v134
	v_cvt_f32_f16_sdwa v25, v134 dst_sel:DWORD dst_unused:UNUSED_PAD src0_sel:WORD_1
	v_permlane32_swap_b32_e32 v128, v132
	v_cvt_f32_f16_sdwa v7, v113 dst_sel:DWORD dst_unused:UNUSED_PAD src0_sel:WORD_1
	v_cvt_f32_f16_e32 v6, v113
	v_cvt_f32_f16_sdwa v9, v110 dst_sel:DWORD dst_unused:UNUSED_PAD src0_sel:WORD_1
	v_cvt_f32_f16_e32 v8, v110
	v_cvt_f32_f16_e32 v26, v128
	v_cvt_f32_f16_sdwa v27, v128 dst_sel:DWORD dst_unused:UNUSED_PAD src0_sel:WORD_1
	v_cvt_f32_f16_e32 v76, v132
	v_cvt_f32_f16_sdwa v77, v132 dst_sel:DWORD dst_unused:UNUSED_PAD src0_sel:WORD_1
	v_pk_add_f32 v[14:15], v[14:15], v[16:17]
	v_pk_add_f32 v[16:17], v[18:19], v[20:21]
	v_pk_add_f32 v[18:19], v[22:23], v[24:25]
	v_pk_mul_f32 v[16:17], v[16:17], s[16:17] op_sel_hi:[1,0]
	v_pk_mul_f32 v[18:19], v[18:19], s[16:17] op_sel_hi:[1,0]
	v_permlane32_swap_b32_e32 v125, v126
	v_cvt_f32_f16_sdwa v11, v111 dst_sel:DWORD dst_unused:UNUSED_PAD src0_sel:WORD_1
	v_cvt_f32_f16_e32 v10, v111
	v_pk_mul_f32 v[16:17], v[70:71], v[16:17]
	v_pk_mul_f32 v[18:19], v[72:73], v[18:19]
	v_pk_add_f32 v[20:21], v[26:27], v[76:77]
	v_pk_fma_f32 v[6:7], v[6:7], s[18:19], v[16:17] op_sel_hi:[1,0,1]
	v_pk_fma_f32 v[8:9], v[8:9], s[18:19], v[18:19] op_sel_hi:[1,0,1]
	v_cvt_f32_f16_e32 v16, v125
	v_cvt_f32_f16_sdwa v17, v125 dst_sel:DWORD dst_unused:UNUSED_PAD src0_sel:WORD_1
	v_cvt_f32_f16_e32 v18, v126
	v_cvt_f32_f16_sdwa v19, v126 dst_sel:DWORD dst_unused:UNUSED_PAD src0_sel:WORD_1
	v_pk_mul_f32 v[20:21], v[20:21], s[16:17] op_sel_hi:[1,0]
	v_permlane32_swap_b32_e32 v127, v130
	v_pk_mul_f32 v[20:21], v[74:75], v[20:21]
	v_cvt_f32_f16_sdwa v5, v112 dst_sel:DWORD dst_unused:UNUSED_PAD src0_sel:WORD_1
	v_cvt_f32_f16_e32 v4, v112
	v_cvt_f32_f16_e32 v78, v127
	v_cvt_f32_f16_sdwa v79, v127 dst_sel:DWORD dst_unused:UNUSED_PAD src0_sel:WORD_1
	v_cvt_f32_f16_e32 v80, v130
	v_cvt_f32_f16_sdwa v81, v130 dst_sel:DWORD dst_unused:UNUSED_PAD src0_sel:WORD_1
	v_pk_fma_f32 v[10:11], v[10:11], s[18:19], v[20:21] op_sel_hi:[1,0,1]
	v_cvt_f32_f16_sdwa v21, v109 dst_sel:DWORD dst_unused:UNUSED_PAD src0_sel:WORD_1
	v_cvt_f32_f16_e32 v20, v109
	v_pk_add_f32 v[16:17], v[16:17], v[18:19]
	v_pk_mul_f32 v[14:15], v[14:15], s[16:17] op_sel_hi:[1,0]
	v_pk_mul_f32 v[16:17], v[16:17], s[16:17] op_sel_hi:[1,0]
	v_permlane32_swap_b32_e32 v123, v124
	v_lshlrev_b64 v[2:3], 12, v[94:95]
	v_cvt_f32_f16_sdwa v13, v108 dst_sel:DWORD dst_unused:UNUSED_PAD src0_sel:WORD_1
	v_cvt_f32_f16_e32 v12, v108
	v_pk_mul_f32 v[14:15], v[68:69], v[14:15]
	v_pk_mul_f32 v[16:17], v[66:67], v[16:17]
	v_lshl_add_u64 v[0:1], v[114:115], 2, s[8:9]
	v_lshl_add_u64 v[2:3], s[6:7], 0, v[2:3]
	v_pk_add_f32 v[22:23], v[78:79], v[80:81]
	v_pk_fma_f32 v[4:5], v[4:5], s[18:19], v[14:15] op_sel_hi:[1,0,1]
	v_pk_fma_f32 v[16:17], v[20:21], s[18:19], v[16:17] op_sel_hi:[1,0,1]
	v_cvt_f32_f16_e32 v18, v123
	v_cvt_f32_f16_sdwa v19, v123 dst_sel:DWORD dst_unused:UNUSED_PAD src0_sel:WORD_1
	v_cvt_f32_f16_e32 v20, v124
	v_cvt_f32_f16_sdwa v21, v124 dst_sel:DWORD dst_unused:UNUSED_PAD src0_sel:WORD_1
	v_cndmask_b32_e64 v1, v3, v1, s[0:1]
	v_pk_mul_f32 v[22:23], v[22:23], s[16:17] op_sel_hi:[1,0]
	v_add_f32_e32 v3, 0, v4
	v_pk_mul_f32 v[22:23], v[64:65], v[22:23]
	v_add_f32_e32 v3, v5, v3
	v_pk_fma_f32 v[12:13], v[12:13], s[18:19], v[22:23] op_sel_hi:[1,0,1]
	v_add_f32_e32 v3, v6, v3
	v_cvt_f32_f16_sdwa v23, v106 dst_sel:DWORD dst_unused:UNUSED_PAD src0_sel:WORD_1
	v_cvt_f32_f16_e32 v22, v106
	v_add_f32_e32 v3, v7, v3
	v_pk_add_f32 v[18:19], v[18:19], v[20:21]
	v_add_f32_e32 v3, v8, v3
	v_pk_mul_f32 v[18:19], v[18:19], s[16:17] op_sel_hi:[1,0]
	v_permlane32_swap_b32_e32 v121, v122
	v_add_f32_e32 v3, v9, v3
	v_pk_mul_f32 v[18:19], v[60:61], v[18:19]
	v_add_f32_e32 v3, v10, v3
	v_pk_fma_f32 v[18:19], v[22:23], s[18:19], v[18:19] op_sel_hi:[1,0,1]
	v_cvt_f32_f16_e32 v20, v121
	v_cvt_f32_f16_sdwa v21, v121 dst_sel:DWORD dst_unused:UNUSED_PAD src0_sel:WORD_1
	v_cvt_f32_f16_e32 v22, v122
	v_cvt_f32_f16_sdwa v23, v122 dst_sel:DWORD dst_unused:UNUSED_PAD src0_sel:WORD_1
	v_add_f32_e32 v3, v11, v3
	v_add_f32_e32 v3, v12, v3
	v_add_f32_e32 v3, v13, v3
	v_cvt_f32_f16_sdwa v25, v107 dst_sel:DWORD dst_unused:UNUSED_PAD src0_sel:WORD_1
	v_cvt_f32_f16_e32 v24, v107
	v_add_f32_e32 v3, v16, v3
	v_pk_add_f32 v[20:21], v[20:21], v[22:23]
	v_add_f32_e32 v3, v17, v3
	v_pk_mul_f32 v[20:21], v[20:21], s[16:17] op_sel_hi:[1,0]
	v_add_f32_e32 v3, v18, v3
	v_pk_mul_f32 v[20:21], v[62:63], v[20:21]
	v_add_f32_e32 v3, v19, v3
	v_pk_fma_f32 v[20:21], v[24:25], s[18:19], v[20:21] op_sel_hi:[1,0,1]
	s_waitcnt vmcnt(0)
	v_cmp_neq_f32_e32 vcc, 0, v82
	v_add_f32_e32 v3, v20, v3
	v_add_f32_e32 v3, v21, v3
	v_mov_b32_e32 v15, v3
	s_nop 1
	v_permlane32_swap_b32_e32 v3, v15
	v_add_f32_e32 v3, v3, v15
	v_mov_b32_e32 v15, v3
	s_nop 1
	v_permlane16_swap_b32_e32 v3, v15
	v_add_f32_e32 v3, v3, v15
	v_cndmask_b32_e32 v14, 0, v120, vcc
	v_cndmask_b32_e64 v0, v2, v0, s[0:1]
	v_add_f32_dpp v3, v3, v3 row_ror:8 row_mask:0xf bank_mask:0xf bound_ctrl:1
	v_mov_b32_e32 v101, v95
	s_nop 0
	v_add_f32_dpp v3, v3, v3 row_ror:4 row_mask:0xf bank_mask:0xf bound_ctrl:1
	s_nop 1
	v_add_f32_dpp v3, v3, v3 quad_perm:[2,3,0,1] row_mask:0xf bank_mask:0xf bound_ctrl:1
	s_nop 1
	v_add_f32_dpp v3, v3, v3 quad_perm:[1,0,3,2] row_mask:0xf bank_mask:0xf bound_ctrl:1
	v_mul_f32_e32 v22, 0x3a800000, v3
	v_pk_add_f32 v[4:5], v[4:5], v[22:23] op_sel_hi:[1,0] neg_lo:[0,1] neg_hi:[0,1]
	v_pk_add_f32 v[6:7], v[6:7], v[22:23] op_sel_hi:[1,0] neg_lo:[0,1] neg_hi:[0,1]
	v_mul_f32_e32 v24, v5, v5
	v_pk_fma_f32 v[24:25], v[4:5], v[4:5], v[24:25] op_sel_hi:[1,1,0]
	v_mul_f32_e32 v26, v7, v7
	v_pk_fma_f32 v[24:25], v[6:7], v[6:7], v[24:25]
	v_pk_add_f32 v[8:9], v[8:9], v[22:23] op_sel_hi:[1,0] neg_lo:[0,1] neg_hi:[0,1]
	v_pk_add_f32 v[24:25], v[26:27], v[24:25] op_sel_hi:[0,1]
	v_pk_fma_f32 v[24:25], v[8:9], v[8:9], v[24:25]
	v_mul_f32_e32 v26, v9, v9
	v_pk_add_f32 v[24:25], v[26:27], v[24:25] op_sel_hi:[0,1]
	v_pk_add_f32 v[10:11], v[10:11], v[22:23] op_sel_hi:[1,0] neg_lo:[0,1] neg_hi:[0,1]
	v_pk_add_f32 v[12:13], v[12:13], v[22:23] op_sel_hi:[1,0] neg_lo:[0,1] neg_hi:[0,1]
	v_pk_fma_f32 v[24:25], v[10:11], v[10:11], v[24:25]
	v_mul_f32_e32 v26, v11, v11
	v_pk_add_f32 v[24:25], v[26:27], v[24:25] op_sel_hi:[0,1]
	v_pk_fma_f32 v[24:25], v[12:13], v[12:13], v[24:25]
	v_mul_f32_e32 v26, v13, v13
	v_pk_add_f32 v[24:25], v[26:27], v[24:25] op_sel_hi:[0,1]
	v_pk_add_f32 v[16:17], v[16:17], v[22:23] op_sel_hi:[1,0] neg_lo:[0,1] neg_hi:[0,1]
	v_pk_add_f32 v[18:19], v[18:19], v[22:23] op_sel_hi:[1,0] neg_lo:[0,1] neg_hi:[0,1]
	v_pk_fma_f32 v[24:25], v[16:17], v[16:17], v[24:25]
	v_mul_f32_e32 v26, v17, v17
	v_pk_add_f32 v[24:25], v[26:27], v[24:25] op_sel_hi:[0,1]
	v_pk_fma_f32 v[24:25], v[18:19], v[18:19], v[24:25]
	v_mul_f32_e32 v26, v19, v19
	v_pk_add_f32 v[24:25], v[26:27], v[24:25] op_sel_hi:[0,1]
	v_pk_add_f32 v[20:21], v[20:21], v[22:23] op_sel_hi:[1,0] neg_lo:[0,1] neg_hi:[0,1]
	s_nop 0
	v_pk_fma_f32 v[22:23], v[20:21], v[20:21], v[24:25]
	v_mul_f32_e32 v24, v21, v21
	v_pk_add_f32 v[22:23], v[24:25], v[22:23] op_sel_hi:[0,1]
	v_mov_b32_e32 v3, v22
	s_nop 1
	v_permlane32_swap_b32_e32 v22, v3
	v_add_f32_e32 v3, v22, v3
	v_mov_b32_e32 v15, v3
	s_nop 1
	v_permlane16_swap_b32_e32 v3, v15
	v_add_f32_e32 v3, v3, v15
	v_lshl_add_u64 v[22:23], v[0:1], 0, v[100:101]
	s_nop 0
	v_add_f32_dpp v3, v3, v3 row_ror:8 row_mask:0xf bank_mask:0xf bound_ctrl:1
	s_nop 1
	v_add_f32_dpp v3, v3, v3 row_ror:4 row_mask:0xf bank_mask:0xf bound_ctrl:1
	s_nop 1
	v_add_f32_dpp v3, v3, v3 quad_perm:[2,3,0,1] row_mask:0xf bank_mask:0xf bound_ctrl:1
	s_nop 1
	v_add_f32_dpp v3, v3, v3 quad_perm:[1,0,3,2] row_mask:0xf bank_mask:0xf bound_ctrl:1
	v_fmamk_f32 v3, v3, 0x3a800000, v119
	v_mul_f32_e32 v15, 0x4b800000, v3
	v_cmp_gt_f32_e32 vcc, s23, v3
	s_nop 1
	v_cndmask_b32_e32 v3, v3, v15, vcc
	v_rsq_f32_e32 v3, v3
	s_nop 0
	v_mul_f32_e32 v0, 0x45800000, v3
	v_cndmask_b32_e32 v24, v3, v0, vcc
	v_pk_mul_f32 v[0:1], v[6:7], v[24:25] op_sel_hi:[1,0]
	v_pk_mul_f32 v[2:3], v[4:5], v[24:25] op_sel_hi:[1,0]
	v_pk_fma_f32 v[0:1], v[58:59], v[0:1], v[54:55]
	v_pk_fma_f32 v[4:5], v[56:57], v[2:3], v[52:53]
	v_pk_add_f32 v[2:3], v[14:15], v[0:1] op_sel_hi:[0,1]
	v_pk_add_f32 v[0:1], v[14:15], v[4:5] op_sel_hi:[0,1]
	global_store_dwordx4 v[22:23], v[0:3], off
	s_nop 1
	v_pk_mul_f32 v[0:1], v[10:11], v[24:25] op_sel_hi:[1,0]
	v_pk_mul_f32 v[2:3], v[8:9], v[24:25] op_sel_hi:[1,0]
	v_pk_fma_f32 v[0:1], v[50:51], v[0:1], v[46:47]
	v_pk_fma_f32 v[4:5], v[48:49], v[2:3], v[44:45]
	v_pk_add_f32 v[2:3], v[14:15], v[0:1] op_sel_hi:[0,1]
	v_pk_add_f32 v[0:1], v[14:15], v[4:5] op_sel_hi:[0,1]
	global_store_dwordx4 v[22:23], v[0:3], off offset:512
	s_nop 1
	v_pk_mul_f32 v[0:1], v[16:17], v[24:25] op_sel_hi:[1,0]
	v_pk_mul_f32 v[2:3], v[12:13], v[24:25] op_sel_hi:[1,0]
	v_pk_fma_f32 v[0:1], v[42:43], v[0:1], v[38:39]
	v_pk_fma_f32 v[4:5], v[40:41], v[2:3], v[36:37]
	v_pk_add_f32 v[2:3], v[14:15], v[0:1] op_sel_hi:[0,1]
	v_pk_add_f32 v[0:1], v[14:15], v[4:5] op_sel_hi:[0,1]
	global_store_dwordx4 v[22:23], v[0:3], off offset:1024
	s_nop 1
	v_pk_mul_f32 v[0:1], v[20:21], v[24:25] op_sel_hi:[1,0]
	v_pk_mul_f32 v[2:3], v[18:19], v[24:25] op_sel_hi:[1,0]
	v_pk_fma_f32 v[0:1], v[34:35], v[0:1], v[30:31]
	v_pk_fma_f32 v[4:5], v[32:33], v[2:3], v[28:29]
	v_pk_add_f32 v[2:3], v[14:15], v[0:1] op_sel_hi:[0,1]
	v_pk_add_f32 v[0:1], v[14:15], v[4:5] op_sel_hi:[0,1]
	global_store_dwordx4 v[22:23], v[0:3], off offset:1536
	s_branch .Lg2_next
.Lg2_save:
	s_setprio 0
	ds_write2st64_b32 v227, v121, v122 offset0:0 offset1:1
	ds_write2st64_b32 v227, v123, v124 offset0:2 offset1:3
	ds_write2st64_b32 v227, v125, v126 offset0:4 offset1:5
	ds_write2st64_b32 v227, v127, v128 offset0:6 offset1:7
	ds_write2st64_b32 v227, v129, v130 offset0:8 offset1:9
	ds_write2st64_b32 v227, v131, v132 offset0:10 offset1:11
	ds_write2st64_b32 v227, v133, v134 offset0:12 offset1:13
	ds_write2st64_b32 v227, v135, v136 offset0:14 offset1:15
